# v35 + FFN-up/w_in batched heads regenerated: LDS reads first, dead bpermute address set-up dropped, cross-lane stages batched over the 8 rows (no per-row s_nop), direct v_rsq
# speedup vs baseline: 1.0046x; 1.0020x over previous
; __device__ __forceinline__ float fast_sigmoid(float x) { return __builtin_amdgcn_rcpf(1.f + __expf(-x)); }
; __device__ __forceinline__ float row_ssq(const float* part, int pitch, int n4, int row, int fq) {
;     f32x4 v = (f32x4){0.f, 0.f, 0.f, 0.f};
;     if (fq < n4) v = *(const f32x4*)(part + (size_t)row * pitch + 4 * fq);
;     float s = (v[0] + v[1]) + (v[2] + v[3]);
;     s += __shfl_xor(s, 16); s += __shfl_xor(s, 32);
;     return s;
; }
;     __device__ __forceinline__ void operator()(const f32x4 (&acc)[2][2][4][2], const Unit& u, int wr, int wc, int fr, int fq) const {
;         const int row0 = u.pm * BM + wr * 64 + fr, col0 = u.pn * 128 + wc * 32 + 8 * fq;
; #pragma unroll
;         for (int ai = 0; ai < 2; ++ai)
; #pragma unroll
;             for (int m = 0; m < 4; ++m) {
;                 const int row = row0 + ai * HALF + m * 16;
;                 const float rs = rsqrtf(row_ssq(ssq, 16, 4, row, fq) * (1.f / 1024.f) + EPS);
;                 float r[8];
; #pragma unroll
;                 for (int n = 0; n < 2; ++n)
; #pragma unroll
;                     for (int e = 0; e < 4; ++e) { const float gv = acc[ai][0][m][n][e] * rs, uv = acc[ai][1][m][n][e] * rs; r[n * 4 + e] = gv * fast_sigmoid(gv) * uv; }
.LBB0_168:
	v_and_b32_e32 v166, 48, v241
	v_lshl_add_u32 v166, v146, 6, v166
	v_add_u32_e32 v166, 0x24000, v166
	ds_read_b128 v[168:171], v166
	ds_read_b128 v[172:175], v166 offset:1024
	ds_read_b128 v[176:179], v166 offset:2048
	ds_read_b128 v[180:183], v166 offset:3072
	ds_read_b128 v[184:187], v166 offset:8192
	ds_read_b128 v[188:191], v166 offset:9216
	ds_read_b128 v[192:195], v166 offset:10240
	ds_read_b128 v[196:199], v166 offset:11264
	v_lshl_add_u32 v144, s44, 8, v146
	v_lshl_or_b32 v142, s4, 7, v148
	v_ashrrev_i32_e32 v143, 31, v142
	v_lshl_add_u64 v[142:143], v[142:143], 1, s[96:97]
	s_movk_i32 s4, 0x1600
	s_mov_b64 s[24:25], -1
	s_waitcnt lgkmcnt(7)
	v_add_f32_e32 v168, v169, v168
	v_add_f32_e32 v170, v170, v171
	v_add_f32_e32 v168, v168, v170
	v_mov_b32_e32 v169, v168
	s_waitcnt lgkmcnt(6)
	v_add_f32_e32 v172, v173, v172
	v_add_f32_e32 v174, v174, v175
	v_add_f32_e32 v172, v172, v174
	v_mov_b32_e32 v173, v172
	s_waitcnt lgkmcnt(5)
	v_add_f32_e32 v176, v177, v176
	v_add_f32_e32 v178, v178, v179
	v_add_f32_e32 v176, v176, v178
	v_mov_b32_e32 v177, v176
	s_waitcnt lgkmcnt(4)
	v_add_f32_e32 v180, v181, v180
	v_add_f32_e32 v182, v182, v183
	v_add_f32_e32 v180, v180, v182
	v_mov_b32_e32 v181, v180
	s_waitcnt lgkmcnt(3)
	v_add_f32_e32 v184, v185, v184
	v_add_f32_e32 v186, v186, v187
	v_add_f32_e32 v184, v184, v186
	v_mov_b32_e32 v185, v184
	s_waitcnt lgkmcnt(2)
	v_add_f32_e32 v188, v189, v188
	v_add_f32_e32 v190, v190, v191
	v_add_f32_e32 v188, v188, v190
	v_mov_b32_e32 v189, v188
	s_waitcnt lgkmcnt(1)
	v_add_f32_e32 v192, v193, v192
	v_add_f32_e32 v194, v194, v195
	v_add_f32_e32 v192, v192, v194
	v_mov_b32_e32 v193, v192
	s_waitcnt lgkmcnt(0)
	v_add_f32_e32 v196, v197, v196
	v_add_f32_e32 v198, v198, v199
	v_add_f32_e32 v196, v196, v198
	v_mov_b32_e32 v197, v196
	s_nop 1
	v_permlane16_swap_b32_e32 v168, v169
	v_permlane16_swap_b32_e32 v172, v173
	v_permlane16_swap_b32_e32 v176, v177
	v_permlane16_swap_b32_e32 v180, v181
	v_permlane16_swap_b32_e32 v184, v185
	v_permlane16_swap_b32_e32 v188, v189
	v_permlane16_swap_b32_e32 v192, v193
	v_permlane16_swap_b32_e32 v196, v197
	v_add_f32_e32 v168, v168, v169
	v_add_f32_e32 v172, v172, v173
	v_add_f32_e32 v176, v176, v177
	v_add_f32_e32 v180, v180, v181
	v_add_f32_e32 v184, v184, v185
	v_add_f32_e32 v188, v188, v189
	v_add_f32_e32 v192, v192, v193
	v_add_f32_e32 v196, v196, v197
	v_mov_b32_e32 v169, v168
	v_mov_b32_e32 v173, v172
	v_mov_b32_e32 v177, v176
	v_mov_b32_e32 v181, v180
	v_mov_b32_e32 v185, v184
	v_mov_b32_e32 v189, v188
	v_mov_b32_e32 v193, v192
	v_mov_b32_e32 v197, v196
	s_nop 1
	v_permlane32_swap_b32_e32 v168, v169
	v_permlane32_swap_b32_e32 v172, v173
	v_permlane32_swap_b32_e32 v176, v177
	v_permlane32_swap_b32_e32 v180, v181
	v_permlane32_swap_b32_e32 v184, v185
	v_permlane32_swap_b32_e32 v188, v189
	v_permlane32_swap_b32_e32 v192, v193
	v_permlane32_swap_b32_e32 v196, v197
	v_add_f32_e32 v168, v168, v169
	v_add_f32_e32 v172, v172, v173
	v_add_f32_e32 v176, v176, v177
	v_add_f32_e32 v180, v180, v181
	v_add_f32_e32 v184, v184, v185
	v_add_f32_e32 v188, v188, v189
	v_add_f32_e32 v192, v192, v193
	v_add_f32_e32 v196, v196, v197
	v_fmamk_f32 v168, v168, 0x3a800000, v239
	v_fmamk_f32 v172, v172, 0x3a800000, v239
	v_fmamk_f32 v176, v176, 0x3a800000, v239
	v_fmamk_f32 v180, v180, 0x3a800000, v239
	v_fmamk_f32 v184, v184, 0x3a800000, v239
	v_fmamk_f32 v188, v188, 0x3a800000, v239
	v_fmamk_f32 v192, v192, 0x3a800000, v239
	v_fmamk_f32 v196, v196, 0x3a800000, v239
	v_rsq_f32_e32 v158, v168
	v_rsq_f32_e32 v159, v172
	v_rsq_f32_e32 v160, v176
	v_rsq_f32_e32 v161, v180
	v_rsq_f32_e32 v162, v184
	v_rsq_f32_e32 v163, v188
	v_rsq_f32_e32 v164, v192
	v_rsq_f32_e32 v165, v196
	s_nop 0
	v_mov_b32_e32 v152, v158
	v_pk_mul_f32 v[126:127], v[126:127], v[152:153] op_sel_hi:[1,0]
	v_pk_mul_f32 v[118:119], v[118:119], v[152:153] op_sel_hi:[1,0]
	v_mul_f32_e32 v145, 0xbfb8aa3b, v126
	v_exp_f32_e32 v145, v145
	v_pk_mul_f32 v[120:121], v[120:121], v[152:153] op_sel_hi:[1,0]
	v_pk_mul_f32 v[122:123], v[122:123], v[152:153] op_sel_hi:[1,0]
	v_pk_mul_f32 v[114:115], v[114:115], v[152:153] op_sel_hi:[1,0]
	v_add_f32_e32 v145, 1.0, v145
	v_rcp_f32_e32 v154, v145
	v_mul_f32_e32 v145, 0xbfb8aa3b, v127
	v_exp_f32_e32 v145, v145
	v_pk_mul_f32 v[116:117], v[116:117], v[152:153] op_sel_hi:[1,0]
	v_add_f32_e32 v145, 1.0, v145
	v_rcp_f32_e32 v155, v145
	s_nop 0
	v_pk_mul_f32 v[126:127], v[126:127], v[154:155]
	s_nop 0
	v_pk_mul_f32 v[118:119], v[118:119], v[126:127]
	v_pk_mul_f32 v[126:127], v[128:129], v[152:153] op_sel_hi:[1,0]
	s_nop 0
	v_mul_f32_e32 v128, 0xbfb8aa3b, v126
	v_mul_f32_e32 v129, 0xbfb8aa3b, v127
	v_exp_f32_e32 v128, v128
	v_exp_f32_e32 v129, v129
	v_add_f32_e32 v128, 1.0, v128
	v_add_f32_e32 v129, 1.0, v129
	v_rcp_f32_e32 v128, v128
	v_rcp_f32_e32 v129, v129
	s_nop 0
	v_pk_mul_f32 v[126:127], v[126:127], v[128:129]
	s_nop 0
	v_pk_mul_f32 v[120:121], v[120:121], v[126:127]
	v_mul_f32_e32 v126, 0xbfb8aa3b, v122
	v_mul_f32_e32 v127, 0xbfb8aa3b, v123
	v_exp_f32_e32 v126, v126
	v_exp_f32_e32 v127, v127
	v_add_f32_e32 v126, 1.0, v126
	v_add_f32_e32 v127, 1.0, v127
	v_rcp_f32_e32 v126, v126
	v_rcp_f32_e32 v127, v127
	s_nop 0
	v_pk_mul_f32 v[122:123], v[122:123], v[126:127]
	s_nop 0
	v_pk_mul_f32 v[122:123], v[114:115], v[122:123]
	v_pk_mul_f32 v[114:115], v[124:125], v[152:153] op_sel_hi:[1,0]
	s_nop 0
	v_mul_f32_e32 v124, 0xbfb8aa3b, v114
	v_mul_f32_e32 v125, 0xbfb8aa3b, v115
	v_exp_f32_e32 v124, v124
	v_exp_f32_e32 v125, v125
	v_add_f32_e32 v124, 1.0, v124
	v_add_f32_e32 v125, 1.0, v125
	v_rcp_f32_e32 v124, v124
	v_rcp_f32_e32 v125, v125
	s_nop 0
	v_pk_mul_f32 v[114:115], v[114:115], v[124:125]
; __device__ __forceinline__ unsigned pk2(float lo, float hi) { f32x2_t v = {lo, hi}; bf16x2_t b = __builtin_convertvector(v, bf16x2_t); return __builtin_bit_cast(unsigned, b); }
; __device__ __forceinline__ float fast_sigmoid(float x) { return __builtin_amdgcn_rcpf(1.f + __expf(-x)); }
;     __device__ __forceinline__ void operator()(const f32x4 (&acc)[2][2][4][2], const Unit& u, int wr, int wc, int fr, int fq) const {
;     ...
;                 for (int n = 0; n < 2; ++n)
; #pragma unroll
;                     for (int e = 0; e < 4; ++e) { const float gv = acc[ai][0][m][n][e] * rs, uv = acc[ai][1][m][n][e] * rs; r[n * 4 + e] = gv * fast_sigmoid(gv) * uv; }
;                 u32x4 w; w.x = pk2(r[0], r[1]); w.y = pk2(r[2], r[3]); w.z = pk2(r[4], r[5]); w.w = pk2(r[6], r[7]);
;                 *(u32x4*)(O + (size_t)row * DFF + col0) = w;
	s_nop 0
	v_pk_mul_f32 v[124:125], v[116:117], v[114:115]
	v_cvt_pk_bf16_f32 v114, v118, v119
	v_cvt_pk_bf16_f32 v115, v120, v121
	v_cvt_pk_bf16_f32 v116, v122, v123
	v_cvt_pk_bf16_f32 v117, v124, v125
	v_mad_i64_i32 v[118:119], s[6:7], v144, s4, v[142:143]
	global_store_dwordx4 v[118:119], v[114:117], off
	s_nop 1
	v_or_b32_e32 v114, 16, v144
	v_mov_b32_e32 v116, v159
	v_pk_mul_f32 v[110:111], v[110:111], v[116:117] op_sel_hi:[1,0]
	v_pk_mul_f32 v[102:103], v[102:103], v[116:117] op_sel_hi:[1,0]
	v_mul_f32_e32 v115, 0xbfb8aa3b, v110
	v_exp_f32_e32 v115, v115
	v_pk_mul_f32 v[104:105], v[104:105], v[116:117] op_sel_hi:[1,0]
	v_pk_mul_f32 v[106:107], v[106:107], v[116:117] op_sel_hi:[1,0]
	v_pk_mul_f32 v[98:99], v[98:99], v[116:117] op_sel_hi:[1,0]
	v_add_f32_e32 v115, 1.0, v115
	v_rcp_f32_e32 v118, v115
	v_mul_f32_e32 v115, 0xbfb8aa3b, v111
	v_exp_f32_e32 v115, v115
	v_pk_mul_f32 v[100:101], v[100:101], v[116:117] op_sel_hi:[1,0]
	v_add_f32_e32 v115, 1.0, v115
	v_rcp_f32_e32 v119, v115
	s_nop 0
	v_pk_mul_f32 v[110:111], v[110:111], v[118:119]
	s_nop 0
	v_pk_mul_f32 v[102:103], v[102:103], v[110:111]
	v_pk_mul_f32 v[110:111], v[112:113], v[116:117] op_sel_hi:[1,0]
	s_nop 0
	v_mul_f32_e32 v112, 0xbfb8aa3b, v110
	v_mul_f32_e32 v113, 0xbfb8aa3b, v111
	v_exp_f32_e32 v112, v112
	v_exp_f32_e32 v113, v113
	v_add_f32_e32 v112, 1.0, v112
	v_add_f32_e32 v113, 1.0, v113
	v_rcp_f32_e32 v112, v112
	v_rcp_f32_e32 v113, v113
	s_nop 0
	v_pk_mul_f32 v[110:111], v[110:111], v[112:113]
	s_nop 0
	v_pk_mul_f32 v[104:105], v[104:105], v[110:111]
	v_mul_f32_e32 v110, 0xbfb8aa3b, v106
	v_mul_f32_e32 v111, 0xbfb8aa3b, v107
	v_exp_f32_e32 v110, v110
	v_exp_f32_e32 v111, v111
	v_add_f32_e32 v110, 1.0, v110
	v_add_f32_e32 v111, 1.0, v111
	v_rcp_f32_e32 v110, v110
	v_rcp_f32_e32 v111, v111
	s_nop 0
	v_pk_mul_f32 v[106:107], v[106:107], v[110:111]
	s_nop 0
	v_pk_mul_f32 v[106:107], v[98:99], v[106:107]
	v_pk_mul_f32 v[98:99], v[108:109], v[116:117] op_sel_hi:[1,0]
	s_nop 0
	v_mul_f32_e32 v108, 0xbfb8aa3b, v98
	v_mul_f32_e32 v109, 0xbfb8aa3b, v99
	v_exp_f32_e32 v108, v108
	v_exp_f32_e32 v109, v109
	v_add_f32_e32 v108, 1.0, v108
	v_add_f32_e32 v109, 1.0, v109
	v_rcp_f32_e32 v108, v108
	v_rcp_f32_e32 v109, v109
	s_nop 0
	v_pk_mul_f32 v[98:99], v[98:99], v[108:109]
	s_nop 0
	v_pk_mul_f32 v[108:109], v[100:101], v[98:99]
	v_cvt_pk_bf16_f32 v98, v102, v103
	v_cvt_pk_bf16_f32 v99, v104, v105
	v_cvt_pk_bf16_f32 v100, v106, v107
	v_cvt_pk_bf16_f32 v101, v108, v109
	v_mad_i64_i32 v[102:103], s[6:7], v114, s4, v[142:143]
	global_store_dwordx4 v[102:103], v[98:101], off
	s_nop 1
	v_or_b32_e32 v98, 32, v144
	v_mov_b32_e32 v100, v160
	v_pk_mul_f32 v[94:95], v[94:95], v[100:101] op_sel_hi:[1,0]
	v_pk_mul_f32 v[86:87], v[86:87], v[100:101] op_sel_hi:[1,0]
	v_mul_f32_e32 v99, 0xbfb8aa3b, v94
	v_exp_f32_e32 v99, v99
	v_pk_mul_f32 v[88:89], v[88:89], v[100:101] op_sel_hi:[1,0]
	v_pk_mul_f32 v[90:91], v[90:91], v[100:101] op_sel_hi:[1,0]
	v_pk_mul_f32 v[82:83], v[82:83], v[100:101] op_sel_hi:[1,0]
	v_add_f32_e32 v99, 1.0, v99
	v_rcp_f32_e32 v102, v99
	v_mul_f32_e32 v99, 0xbfb8aa3b, v95
	v_exp_f32_e32 v99, v99
	v_pk_mul_f32 v[84:85], v[84:85], v[100:101] op_sel_hi:[1,0]
	v_add_f32_e32 v99, 1.0, v99
	v_rcp_f32_e32 v103, v99
	s_nop 0
	v_pk_mul_f32 v[94:95], v[94:95], v[102:103]
	s_nop 0
	v_pk_mul_f32 v[86:87], v[86:87], v[94:95]
	v_pk_mul_f32 v[94:95], v[96:97], v[100:101] op_sel_hi:[1,0]
	s_nop 0
	v_mul_f32_e32 v96, 0xbfb8aa3b, v94
	v_mul_f32_e32 v97, 0xbfb8aa3b, v95
	v_exp_f32_e32 v96, v96
	v_exp_f32_e32 v97, v97
	v_add_f32_e32 v96, 1.0, v96
	v_add_f32_e32 v97, 1.0, v97
	v_rcp_f32_e32 v96, v96
	v_rcp_f32_e32 v97, v97
	s_nop 0
	v_pk_mul_f32 v[94:95], v[94:95], v[96:97]
	s_nop 0
	v_pk_mul_f32 v[88:89], v[88:89], v[94:95]
	v_mul_f32_e32 v94, 0xbfb8aa3b, v90
	v_mul_f32_e32 v95, 0xbfb8aa3b, v91
	v_exp_f32_e32 v94, v94
	v_exp_f32_e32 v95, v95
	v_add_f32_e32 v94, 1.0, v94
	v_add_f32_e32 v95, 1.0, v95
	v_rcp_f32_e32 v94, v94
	v_rcp_f32_e32 v95, v95
	s_nop 0
	v_pk_mul_f32 v[90:91], v[90:91], v[94:95]
	s_nop 0
	v_pk_mul_f32 v[90:91], v[82:83], v[90:91]
	v_pk_mul_f32 v[82:83], v[92:93], v[100:101] op_sel_hi:[1,0]
	s_nop 0
	v_mul_f32_e32 v92, 0xbfb8aa3b, v82
	v_mul_f32_e32 v93, 0xbfb8aa3b, v83
	v_exp_f32_e32 v92, v92
	v_exp_f32_e32 v93, v93
	v_add_f32_e32 v92, 1.0, v92
	v_add_f32_e32 v93, 1.0, v93
	v_rcp_f32_e32 v92, v92
	v_rcp_f32_e32 v93, v93
	s_nop 0
	v_pk_mul_f32 v[82:83], v[82:83], v[92:93]
	s_nop 0
	v_pk_mul_f32 v[92:93], v[84:85], v[82:83]
	v_cvt_pk_bf16_f32 v82, v86, v87
	v_cvt_pk_bf16_f32 v83, v88, v89
	v_cvt_pk_bf16_f32 v84, v90, v91
	v_cvt_pk_bf16_f32 v85, v92, v93
	v_mad_i64_i32 v[86:87], s[6:7], v98, s4, v[142:143]
	global_store_dwordx4 v[86:87], v[82:85], off
	s_nop 1
	v_or_b32_e32 v82, 48, v144
	v_mov_b32_e32 v84, v161
	v_pk_mul_f32 v[78:79], v[78:79], v[84:85] op_sel_hi:[1,0]
	v_pk_mul_f32 v[70:71], v[70:71], v[84:85] op_sel_hi:[1,0]
	v_mul_f32_e32 v83, 0xbfb8aa3b, v78
	v_exp_f32_e32 v83, v83
	v_pk_mul_f32 v[72:73], v[72:73], v[84:85] op_sel_hi:[1,0]
	v_pk_mul_f32 v[74:75], v[74:75], v[84:85] op_sel_hi:[1,0]
	v_pk_mul_f32 v[66:67], v[66:67], v[84:85] op_sel_hi:[1,0]
	v_add_f32_e32 v83, 1.0, v83
	v_rcp_f32_e32 v86, v83
	v_mul_f32_e32 v83, 0xbfb8aa3b, v79
	v_exp_f32_e32 v83, v83
	v_pk_mul_f32 v[68:69], v[68:69], v[84:85] op_sel_hi:[1,0]
	v_add_f32_e32 v83, 1.0, v83
	v_rcp_f32_e32 v87, v83
	s_nop 0
	v_pk_mul_f32 v[78:79], v[78:79], v[86:87]
	s_nop 0
	v_pk_mul_f32 v[70:71], v[70:71], v[78:79]
	v_pk_mul_f32 v[78:79], v[80:81], v[84:85] op_sel_hi:[1,0]
	s_nop 0
	v_mul_f32_e32 v80, 0xbfb8aa3b, v78
	v_mul_f32_e32 v81, 0xbfb8aa3b, v79
	v_exp_f32_e32 v80, v80
	v_exp_f32_e32 v81, v81
; __device__ __forceinline__ unsigned pk2(float lo, float hi) { f32x2_t v = {lo, hi}; bf16x2_t b = __builtin_convertvector(v, bf16x2_t); return __builtin_bit_cast(unsigned, b); }
; __device__ __forceinline__ float fast_sigmoid(float x) { return __builtin_amdgcn_rcpf(1.f + __expf(-x)); }
;     __device__ __forceinline__ void operator()(const f32x4 (&acc)[2][2][4][2], const Unit& u, int wr, int wc, int fr, int fq) const {
;     ...
;                 for (int n = 0; n < 2; ++n)
; #pragma unroll
;                     for (int e = 0; e < 4; ++e) { const float gv = acc[ai][0][m][n][e] * rs, uv = acc[ai][1][m][n][e] * rs; r[n * 4 + e] = gv * fast_sigmoid(gv) * uv; }
;                 u32x4 w; w.x = pk2(r[0], r[1]); w.y = pk2(r[2], r[3]); w.z = pk2(r[4], r[5]); w.w = pk2(r[6], r[7]);
;                 *(u32x4*)(O + (size_t)row * DFF + col0) = w;
	v_add_f32_e32 v80, 1.0, v80
	v_add_f32_e32 v81, 1.0, v81
	v_rcp_f32_e32 v80, v80
	v_rcp_f32_e32 v81, v81
	s_nop 0
	v_pk_mul_f32 v[78:79], v[78:79], v[80:81]
	s_nop 0
	v_pk_mul_f32 v[72:73], v[72:73], v[78:79]
	v_mul_f32_e32 v78, 0xbfb8aa3b, v74
	v_mul_f32_e32 v79, 0xbfb8aa3b, v75
	v_exp_f32_e32 v78, v78
	v_exp_f32_e32 v79, v79
	v_add_f32_e32 v78, 1.0, v78
	v_add_f32_e32 v79, 1.0, v79
	v_rcp_f32_e32 v78, v78
	v_rcp_f32_e32 v79, v79
	s_nop 0
	v_pk_mul_f32 v[74:75], v[74:75], v[78:79]
	s_nop 0
	v_pk_mul_f32 v[74:75], v[66:67], v[74:75]
	v_pk_mul_f32 v[66:67], v[76:77], v[84:85] op_sel_hi:[1,0]
	s_nop 0
	v_mul_f32_e32 v76, 0xbfb8aa3b, v66
	v_mul_f32_e32 v77, 0xbfb8aa3b, v67
	v_exp_f32_e32 v76, v76
	v_exp_f32_e32 v77, v77
	v_add_f32_e32 v76, 1.0, v76
	v_add_f32_e32 v77, 1.0, v77
	v_rcp_f32_e32 v76, v76
	v_rcp_f32_e32 v77, v77
	s_nop 0
	v_pk_mul_f32 v[66:67], v[66:67], v[76:77]
	s_nop 0
	v_pk_mul_f32 v[76:77], v[68:69], v[66:67]
	v_cvt_pk_bf16_f32 v66, v70, v71
	v_cvt_pk_bf16_f32 v67, v72, v73
	v_cvt_pk_bf16_f32 v68, v74, v75
	v_cvt_pk_bf16_f32 v69, v76, v77
	v_mad_i64_i32 v[70:71], s[6:7], v82, s4, v[142:143]
	global_store_dwordx4 v[70:71], v[66:69], off
	s_nop 1
	v_add_u32_e32 v66, 0x80, v144
	v_mov_b32_e32 v68, v162
	v_pk_mul_f32 v[62:63], v[62:63], v[68:69] op_sel_hi:[1,0]
	v_pk_mul_f32 v[54:55], v[54:55], v[68:69] op_sel_hi:[1,0]
	v_mul_f32_e32 v67, 0xbfb8aa3b, v62
	v_exp_f32_e32 v67, v67
	v_pk_mul_f32 v[56:57], v[56:57], v[68:69] op_sel_hi:[1,0]
	v_pk_mul_f32 v[58:59], v[58:59], v[68:69] op_sel_hi:[1,0]
	v_pk_mul_f32 v[50:51], v[50:51], v[68:69] op_sel_hi:[1,0]
	v_add_f32_e32 v67, 1.0, v67
	v_rcp_f32_e32 v70, v67
	v_mul_f32_e32 v67, 0xbfb8aa3b, v63
	v_exp_f32_e32 v67, v67
	v_pk_mul_f32 v[52:53], v[52:53], v[68:69] op_sel_hi:[1,0]
	v_add_f32_e32 v67, 1.0, v67
	v_rcp_f32_e32 v71, v67
	s_nop 0
	v_pk_mul_f32 v[62:63], v[62:63], v[70:71]
	s_nop 0
	v_pk_mul_f32 v[54:55], v[54:55], v[62:63]
	v_pk_mul_f32 v[62:63], v[64:65], v[68:69] op_sel_hi:[1,0]
	s_nop 0
	v_mul_f32_e32 v64, 0xbfb8aa3b, v62
	v_mul_f32_e32 v65, 0xbfb8aa3b, v63
	v_exp_f32_e32 v64, v64
	v_exp_f32_e32 v65, v65
	v_add_f32_e32 v64, 1.0, v64
	v_add_f32_e32 v65, 1.0, v65
	v_rcp_f32_e32 v64, v64
	v_rcp_f32_e32 v65, v65
	s_nop 0
	v_pk_mul_f32 v[62:63], v[62:63], v[64:65]
	s_nop 0
	v_pk_mul_f32 v[56:57], v[56:57], v[62:63]
	v_mul_f32_e32 v62, 0xbfb8aa3b, v58
	v_mul_f32_e32 v63, 0xbfb8aa3b, v59
	v_exp_f32_e32 v62, v62
	v_exp_f32_e32 v63, v63
	v_add_f32_e32 v62, 1.0, v62
	v_add_f32_e32 v63, 1.0, v63
	v_rcp_f32_e32 v62, v62
	v_rcp_f32_e32 v63, v63
	s_nop 0
	v_pk_mul_f32 v[58:59], v[58:59], v[62:63]
	s_nop 0
	v_pk_mul_f32 v[58:59], v[50:51], v[58:59]
	v_pk_mul_f32 v[50:51], v[60:61], v[68:69] op_sel_hi:[1,0]
	s_nop 0
	v_mul_f32_e32 v60, 0xbfb8aa3b, v50
	v_mul_f32_e32 v61, 0xbfb8aa3b, v51
	v_exp_f32_e32 v60, v60
	v_exp_f32_e32 v61, v61
	v_add_f32_e32 v60, 1.0, v60
	v_add_f32_e32 v61, 1.0, v61
	v_rcp_f32_e32 v60, v60
	v_rcp_f32_e32 v61, v61
	s_nop 0
	v_pk_mul_f32 v[50:51], v[50:51], v[60:61]
	s_nop 0
	v_pk_mul_f32 v[60:61], v[52:53], v[50:51]
	v_cvt_pk_bf16_f32 v50, v54, v55
	v_cvt_pk_bf16_f32 v51, v56, v57
	v_cvt_pk_bf16_f32 v52, v58, v59
	v_cvt_pk_bf16_f32 v53, v60, v61
	v_mad_i64_i32 v[54:55], s[6:7], v66, s4, v[142:143]
	global_store_dwordx4 v[54:55], v[50:53], off
	s_nop 1
	v_add_u32_e32 v50, 0x90, v144
	v_mov_b32_e32 v52, v163
	v_pk_mul_f32 v[46:47], v[46:47], v[52:53] op_sel_hi:[1,0]
	v_pk_mul_f32 v[38:39], v[38:39], v[52:53] op_sel_hi:[1,0]
	v_mul_f32_e32 v51, 0xbfb8aa3b, v46
	v_exp_f32_e32 v51, v51
	v_pk_mul_f32 v[40:41], v[40:41], v[52:53] op_sel_hi:[1,0]
	v_pk_mul_f32 v[42:43], v[42:43], v[52:53] op_sel_hi:[1,0]
	v_pk_mul_f32 v[34:35], v[34:35], v[52:53] op_sel_hi:[1,0]
	v_add_f32_e32 v51, 1.0, v51
	v_rcp_f32_e32 v54, v51
	v_mul_f32_e32 v51, 0xbfb8aa3b, v47
	v_exp_f32_e32 v51, v51
	v_pk_mul_f32 v[36:37], v[36:37], v[52:53] op_sel_hi:[1,0]
	v_add_f32_e32 v51, 1.0, v51
	v_rcp_f32_e32 v55, v51
	s_nop 0
	v_pk_mul_f32 v[46:47], v[46:47], v[54:55]
	s_nop 0
	v_pk_mul_f32 v[38:39], v[38:39], v[46:47]
	v_pk_mul_f32 v[46:47], v[48:49], v[52:53] op_sel_hi:[1,0]
	s_nop 0
	v_mul_f32_e32 v48, 0xbfb8aa3b, v46
	v_mul_f32_e32 v49, 0xbfb8aa3b, v47
	v_exp_f32_e32 v48, v48
	v_exp_f32_e32 v49, v49
	v_add_f32_e32 v48, 1.0, v48
	v_add_f32_e32 v49, 1.0, v49
	v_rcp_f32_e32 v48, v48
	v_rcp_f32_e32 v49, v49
	s_nop 0
	v_pk_mul_f32 v[46:47], v[46:47], v[48:49]
	s_nop 0
	v_pk_mul_f32 v[40:41], v[40:41], v[46:47]
	v_mul_f32_e32 v46, 0xbfb8aa3b, v42
	v_mul_f32_e32 v47, 0xbfb8aa3b, v43
	v_exp_f32_e32 v46, v46
	v_exp_f32_e32 v47, v47
	v_add_f32_e32 v46, 1.0, v46
	v_add_f32_e32 v47, 1.0, v47
	v_rcp_f32_e32 v46, v46
	v_rcp_f32_e32 v47, v47
	s_nop 0
	v_pk_mul_f32 v[42:43], v[42:43], v[46:47]
	s_nop 0
	v_pk_mul_f32 v[42:43], v[34:35], v[42:43]
	v_pk_mul_f32 v[34:35], v[44:45], v[52:53] op_sel_hi:[1,0]
	s_nop 0
	v_mul_f32_e32 v44, 0xbfb8aa3b, v34
; __device__ __forceinline__ unsigned pk2(float lo, float hi) { f32x2_t v = {lo, hi}; bf16x2_t b = __builtin_convertvector(v, bf16x2_t); return __builtin_bit_cast(unsigned, b); }
; __device__ __forceinline__ float fast_sigmoid(float x) { return __builtin_amdgcn_rcpf(1.f + __expf(-x)); }
; #define PG8_BAR __builtin_amdgcn_s_barrier()
; template <class Epi>
; __device__ __forceinline__ void gemm_phase(LAS unsigned char* lds, int wave_s, const Gemm g, const StaticOrder S, const Epi E) {
;     ...
;         if (wr == 0) PG8_BAR;
;         E(acc, cur, wr, wc, fr, fq);
;         if (!has_next) break;
; #pragma unroll
;         for (int a = 0; a < 2; ++a)
; #pragma unroll
;             for (int b = 0; b < 2; ++b)
; #pragma unroll
;                 for (int m = 0; m < 4; ++m)
; #pragma unroll
;                     for (int n = 0; n < 2; ++n) acc[a][b][m][n] = (f32x4){0.f, 0.f, 0.f, 0.f};
;         cur = nxt; cA = nA; cB = nB; ++ui;
;         if (wr == 1) PG8_BAR;
;     __device__ __forceinline__ void operator()(const f32x4 (&acc)[2][2][4][2], const Unit& u, int wr, int wc, int fr, int fq) const {
;     ...
;                 for (int n = 0; n < 2; ++n)
; #pragma unroll
;                     for (int e = 0; e < 4; ++e) { const float gv = acc[ai][0][m][n][e] * rs, uv = acc[ai][1][m][n][e] * rs; r[n * 4 + e] = gv * fast_sigmoid(gv) * uv; }
;                 u32x4 w; w.x = pk2(r[0], r[1]); w.y = pk2(r[2], r[3]); w.z = pk2(r[4], r[5]); w.w = pk2(r[6], r[7]);
;                 *(u32x4*)(O + (size_t)row * DFF + col0) = w;
	v_mul_f32_e32 v45, 0xbfb8aa3b, v35
	v_exp_f32_e32 v44, v44
	v_exp_f32_e32 v45, v45
	v_add_f32_e32 v44, 1.0, v44
	v_add_f32_e32 v45, 1.0, v45
	v_rcp_f32_e32 v44, v44
	v_rcp_f32_e32 v45, v45
	s_nop 0
	v_pk_mul_f32 v[34:35], v[34:35], v[44:45]
	s_nop 0
	v_pk_mul_f32 v[44:45], v[36:37], v[34:35]
	v_cvt_pk_bf16_f32 v34, v38, v39
	v_cvt_pk_bf16_f32 v35, v40, v41
	v_cvt_pk_bf16_f32 v36, v42, v43
	v_cvt_pk_bf16_f32 v37, v44, v45
	v_mad_i64_i32 v[38:39], s[6:7], v50, s4, v[142:143]
	global_store_dwordx4 v[38:39], v[34:37], off
	s_nop 1
	v_add_u32_e32 v34, 0xa0, v144
	v_mov_b32_e32 v36, v164
	v_pk_mul_f32 v[30:31], v[30:31], v[36:37] op_sel_hi:[1,0]
	v_pk_mul_f32 v[22:23], v[22:23], v[36:37] op_sel_hi:[1,0]
	v_mul_f32_e32 v35, 0xbfb8aa3b, v30
	v_exp_f32_e32 v35, v35
	v_pk_mul_f32 v[24:25], v[24:25], v[36:37] op_sel_hi:[1,0]
	v_pk_mul_f32 v[26:27], v[26:27], v[36:37] op_sel_hi:[1,0]
	v_pk_mul_f32 v[18:19], v[18:19], v[36:37] op_sel_hi:[1,0]
	v_add_f32_e32 v35, 1.0, v35
	v_rcp_f32_e32 v38, v35
	v_mul_f32_e32 v35, 0xbfb8aa3b, v31
	v_exp_f32_e32 v35, v35
	v_pk_mul_f32 v[20:21], v[20:21], v[36:37] op_sel_hi:[1,0]
	v_add_f32_e32 v35, 1.0, v35
	v_rcp_f32_e32 v39, v35
	s_nop 0
	v_pk_mul_f32 v[30:31], v[30:31], v[38:39]
	s_nop 0
	v_pk_mul_f32 v[22:23], v[22:23], v[30:31]
	v_pk_mul_f32 v[30:31], v[32:33], v[36:37] op_sel_hi:[1,0]
	s_nop 0
	v_mul_f32_e32 v32, 0xbfb8aa3b, v30
	v_mul_f32_e32 v33, 0xbfb8aa3b, v31
	v_exp_f32_e32 v32, v32
	v_exp_f32_e32 v33, v33
	v_add_f32_e32 v32, 1.0, v32
	v_add_f32_e32 v33, 1.0, v33
	v_rcp_f32_e32 v32, v32
	v_rcp_f32_e32 v33, v33
	s_nop 0
	v_pk_mul_f32 v[30:31], v[30:31], v[32:33]
	s_nop 0
	v_pk_mul_f32 v[24:25], v[24:25], v[30:31]
	v_mul_f32_e32 v30, 0xbfb8aa3b, v26
	v_mul_f32_e32 v31, 0xbfb8aa3b, v27
	v_exp_f32_e32 v30, v30
	v_exp_f32_e32 v31, v31
	v_add_f32_e32 v30, 1.0, v30
	v_add_f32_e32 v31, 1.0, v31
	v_rcp_f32_e32 v30, v30
	v_rcp_f32_e32 v31, v31
	s_nop 0
	v_pk_mul_f32 v[26:27], v[26:27], v[30:31]
	s_nop 0
	v_pk_mul_f32 v[26:27], v[18:19], v[26:27]
	v_pk_mul_f32 v[18:19], v[28:29], v[36:37] op_sel_hi:[1,0]
	s_nop 0
	v_mul_f32_e32 v28, 0xbfb8aa3b, v18
	v_mul_f32_e32 v29, 0xbfb8aa3b, v19
	v_exp_f32_e32 v28, v28
	v_exp_f32_e32 v29, v29
	v_add_f32_e32 v28, 1.0, v28
	v_add_f32_e32 v29, 1.0, v29
	v_rcp_f32_e32 v28, v28
	v_rcp_f32_e32 v29, v29
	s_nop 0
	v_pk_mul_f32 v[18:19], v[18:19], v[28:29]
	s_nop 0
	v_pk_mul_f32 v[28:29], v[20:21], v[18:19]
	v_cvt_pk_bf16_f32 v18, v22, v23
	v_cvt_pk_bf16_f32 v19, v24, v25
	v_cvt_pk_bf16_f32 v20, v26, v27
	v_cvt_pk_bf16_f32 v21, v28, v29
	v_mad_i64_i32 v[22:23], s[6:7], v34, s4, v[142:143]
	global_store_dwordx4 v[22:23], v[18:21], off
	s_nop 1
	v_add_u32_e32 v18, 0xb0, v144
	v_mov_b32_e32 v20, v165
	v_pk_mul_f32 v[14:15], v[14:15], v[20:21] op_sel_hi:[1,0]
	v_pk_mul_f32 v[6:7], v[6:7], v[20:21] op_sel_hi:[1,0]
	v_mul_f32_e32 v19, 0xbfb8aa3b, v14
	v_exp_f32_e32 v19, v19
	v_pk_mul_f32 v[8:9], v[8:9], v[20:21] op_sel_hi:[1,0]
	v_pk_mul_f32 v[10:11], v[10:11], v[20:21] op_sel_hi:[1,0]
	v_pk_mul_f32 v[2:3], v[2:3], v[20:21] op_sel_hi:[1,0]
	v_add_f32_e32 v19, 1.0, v19
	v_rcp_f32_e32 v22, v19
	v_mul_f32_e32 v19, 0xbfb8aa3b, v15
	v_exp_f32_e32 v19, v19
	v_pk_mul_f32 v[4:5], v[4:5], v[20:21] op_sel_hi:[1,0]
	s_andn2_b64 vcc, exec, s[0:1]
	v_add_f32_e32 v19, 1.0, v19
	v_rcp_f32_e32 v23, v19
	s_nop 0
	v_pk_mul_f32 v[14:15], v[14:15], v[22:23]
	s_nop 0
	v_pk_mul_f32 v[6:7], v[6:7], v[14:15]
	v_pk_mul_f32 v[14:15], v[16:17], v[20:21] op_sel_hi:[1,0]
	s_nop 0
	v_mul_f32_e32 v16, 0xbfb8aa3b, v14
	v_mul_f32_e32 v17, 0xbfb8aa3b, v15
	v_exp_f32_e32 v16, v16
	v_exp_f32_e32 v17, v17
	v_add_f32_e32 v16, 1.0, v16
	v_add_f32_e32 v17, 1.0, v17
	v_rcp_f32_e32 v16, v16
	v_rcp_f32_e32 v17, v17
	s_nop 0
	v_pk_mul_f32 v[14:15], v[14:15], v[16:17]
	s_nop 0
	v_pk_mul_f32 v[8:9], v[8:9], v[14:15]
	v_mul_f32_e32 v14, 0xbfb8aa3b, v10
	v_mul_f32_e32 v15, 0xbfb8aa3b, v11
	v_exp_f32_e32 v14, v14
	v_exp_f32_e32 v15, v15
	v_add_f32_e32 v14, 1.0, v14
	v_add_f32_e32 v15, 1.0, v15
	v_rcp_f32_e32 v14, v14
	v_rcp_f32_e32 v15, v15
	s_nop 0
	v_pk_mul_f32 v[10:11], v[10:11], v[14:15]
	s_nop 0
	v_pk_mul_f32 v[10:11], v[2:3], v[10:11]
	v_pk_mul_f32 v[2:3], v[12:13], v[20:21] op_sel_hi:[1,0]
	s_nop 0
	v_mul_f32_e32 v12, 0xbfb8aa3b, v2
	v_mul_f32_e32 v13, 0xbfb8aa3b, v3
	v_exp_f32_e32 v12, v12
	v_exp_f32_e32 v13, v13
	v_add_f32_e32 v12, 1.0, v12
	v_add_f32_e32 v13, 1.0, v13
	v_rcp_f32_e32 v12, v12
	v_rcp_f32_e32 v13, v13
	s_nop 0
	v_pk_mul_f32 v[2:3], v[2:3], v[12:13]
	s_nop 0
	v_pk_mul_f32 v[12:13], v[4:5], v[2:3]
	v_cvt_pk_bf16_f32 v2, v6, v7
	v_cvt_pk_bf16_f32 v3, v8, v9
	v_cvt_pk_bf16_f32 v4, v10, v11
	v_cvt_pk_bf16_f32 v5, v12, v13
	v_mad_i64_i32 v[6:7], s[6:7], v18, s4, v[142:143]
	global_store_dwordx4 v[6:7], v[2:5], off
	s_cbranch_vccnz .LBB0_161
	s_andn2_b64 vcc, exec, s[12:13]
	s_cbranch_vccnz .LBB0_160
	s_barrier
	s_branch .LBB0_160

; __device__ __forceinline__ float row_ssq(const float* part, int pitch, int n4, int row, int fq) {
;     f32x4 v = (f32x4){0.f, 0.f, 0.f, 0.f};
;     if (fq < n4) v = *(const f32x4*)(part + (size_t)row * pitch + 4 * fq);
;     float s = (v[0] + v[1]) + (v[2] + v[3]);
;     s += __shfl_xor(s, 16); s += __shfl_xor(s, 32);
;     return s;
; }
;     __device__ __forceinline__ void operator()(const f32x4 (&acc)[2][2][4][2], const Unit& u, int wr, int wc, int fr, int fq) const {
;     ...
;         float rsv[2][4];
; #pragma unroll
;         for (int ai = 0; ai < 2; ++ai)
; #pragma unroll
;             for (int m = 0; m < 4; ++m) rsv[ai][m] = ssq_in ? rsqrtf(row_ssq(ssq_in, in_pitch, in_n4, row0 + ai * HALF + m * 16, fq) * inv_k + EPS) : 1.f;
.LBB0_331:
	v_readlane_b32 s0, v252, 23
	v_readlane_b32 s1, v252, 24
	v_lshl_add_u32 v156, s4, 8, v139
	v_mov_b32_e32 v163, 1.0
	v_cndmask_b32_e64 v0, 0, 1, s[0:1]
	v_cmp_ne_u32_e64 s[50:51], 1, v0
	s_andn2_b64 vcc, exec, s[0:1]
	v_ashrrev_i32_e32 v157, 31, v156
	v_mov_b32_e32 v164, 1.0
	v_mov_b32_e32 v162, 1.0
	v_mov_b32_e32 v161, 1.0
	v_mov_b32_e32 v160, 1.0
	v_mov_b32_e32 v155, 1.0
	v_mov_b32_e32 v153, 1.0
	v_mov_b32_e32 v151, 1.0
	v_or_b32_e32 v154, 16, v156
	v_or_b32_e32 v152, 32, v156
	v_or_b32_e32 v150, 48, v156
	v_add_u32_e32 v148, 0x80, v156
	v_ashrrev_i32_e32 v149, 31, v148
	s_cbranch_vccnz .Lrsv_win_done
	v_and_b32_e32 v166, 48, v241
	v_lshl_add_u32 v166, v139, 6, v166
	v_add_u32_e32 v166, 0x24000, v166
	ds_read_b128 v[168:171], v166
	ds_read_b128 v[172:175], v166 offset:1024
	ds_read_b128 v[176:179], v166 offset:2048
	ds_read_b128 v[180:183], v166 offset:3072
	ds_read_b128 v[184:187], v166 offset:8192
	ds_read_b128 v[188:191], v166 offset:9216
	ds_read_b128 v[192:195], v166 offset:10240
	ds_read_b128 v[196:199], v166 offset:11264
	s_waitcnt lgkmcnt(7)
	v_add_f32_e32 v168, v169, v168
	v_add_f32_e32 v170, v170, v171
	v_add_f32_e32 v168, v168, v170
	v_mov_b32_e32 v169, v168
	s_waitcnt lgkmcnt(6)
	v_add_f32_e32 v172, v173, v172
	v_add_f32_e32 v174, v174, v175
	v_add_f32_e32 v172, v172, v174
	v_mov_b32_e32 v173, v172
	s_waitcnt lgkmcnt(5)
	v_add_f32_e32 v176, v177, v176
	v_add_f32_e32 v178, v178, v179
	v_add_f32_e32 v176, v176, v178
	v_mov_b32_e32 v177, v176
	s_waitcnt lgkmcnt(4)
	v_add_f32_e32 v180, v181, v180
	v_add_f32_e32 v182, v182, v183
	v_add_f32_e32 v180, v180, v182
	v_mov_b32_e32 v181, v180
	s_waitcnt lgkmcnt(3)
	v_add_f32_e32 v184, v185, v184
	v_add_f32_e32 v186, v186, v187
	v_add_f32_e32 v184, v184, v186
	v_mov_b32_e32 v185, v184
	s_waitcnt lgkmcnt(2)
	v_add_f32_e32 v188, v189, v188
	v_add_f32_e32 v190, v190, v191
	v_add_f32_e32 v188, v188, v190
	v_mov_b32_e32 v189, v188
	s_waitcnt lgkmcnt(1)
	v_add_f32_e32 v192, v193, v192
	v_add_f32_e32 v194, v194, v195
	v_add_f32_e32 v192, v192, v194
	v_mov_b32_e32 v193, v192
	s_waitcnt lgkmcnt(0)
	v_add_f32_e32 v196, v197, v196
	v_add_f32_e32 v198, v198, v199
	v_add_f32_e32 v196, v196, v198
	v_mov_b32_e32 v197, v196
	s_nop 1
	v_permlane16_swap_b32_e32 v168, v169
	v_permlane16_swap_b32_e32 v172, v173
	v_permlane16_swap_b32_e32 v176, v177
	v_permlane16_swap_b32_e32 v180, v181
	v_permlane16_swap_b32_e32 v184, v185
	v_permlane16_swap_b32_e32 v188, v189
	v_permlane16_swap_b32_e32 v192, v193
	v_permlane16_swap_b32_e32 v196, v197
	v_add_f32_e32 v168, v168, v169
	v_add_f32_e32 v172, v172, v173
	v_add_f32_e32 v176, v176, v177
	v_add_f32_e32 v180, v180, v181
	v_add_f32_e32 v184, v184, v185
	v_add_f32_e32 v188, v188, v189
	v_add_f32_e32 v192, v192, v193
	v_add_f32_e32 v196, v196, v197
	v_mov_b32_e32 v169, v168
	v_mov_b32_e32 v173, v172
	v_mov_b32_e32 v177, v176
	v_mov_b32_e32 v181, v180
	v_mov_b32_e32 v185, v184
	v_mov_b32_e32 v189, v188
	v_mov_b32_e32 v193, v192
	v_mov_b32_e32 v197, v196
	s_nop 1
	v_permlane32_swap_b32_e32 v168, v169
	v_permlane32_swap_b32_e32 v172, v173
	v_permlane32_swap_b32_e32 v176, v177
	v_permlane32_swap_b32_e32 v180, v181
	v_permlane32_swap_b32_e32 v184, v185
	v_permlane32_swap_b32_e32 v188, v189
	v_permlane32_swap_b32_e32 v192, v193
	v_permlane32_swap_b32_e32 v196, v197
	v_add_f32_e32 v168, v168, v169
	v_add_f32_e32 v172, v172, v173
	v_add_f32_e32 v176, v176, v177
	v_add_f32_e32 v180, v180, v181
	v_add_f32_e32 v184, v184, v185
	v_add_f32_e32 v188, v188, v189
	v_add_f32_e32 v192, v192, v193
	v_add_f32_e32 v196, v196, v197
	v_fmamk_f32 v168, v168, 0x3a800000, v239
	v_fmamk_f32 v172, v172, 0x3a800000, v239
	v_fmamk_f32 v176, v176, 0x3a800000, v239
	v_fmamk_f32 v180, v180, 0x3a800000, v239
	v_fmamk_f32 v184, v184, 0x3a800000, v239
	v_fmamk_f32 v188, v188, 0x3a800000, v239
	v_fmamk_f32 v192, v192, 0x3a800000, v239
	v_fmamk_f32 v196, v196, 0x3a800000, v239
	v_rsq_f32_e32 v164, v168
	v_rsq_f32_e32 v163, v172
	v_rsq_f32_e32 v162, v176
	v_rsq_f32_e32 v161, v180
	v_rsq_f32_e32 v160, v184
	v_rsq_f32_e32 v155, v188
	v_rsq_f32_e32 v153, v192
	v_rsq_f32_e32 v151, v196
	s_nop 0

; __device__ __forceinline__ unsigned pk2(float lo, float hi) { f32x2_t v = {lo, hi}; bf16x2_t b = __builtin_convertvector(v, bf16x2_t); return __builtin_bit_cast(unsigned, b); }
; __device__ __forceinline__ float fast_sigmoid(float x) { return __builtin_amdgcn_rcpf(1.f + __expf(-x)); }
; __device__ __forceinline__ float row_ssq(const float* part, int pitch, int n4, int row, int fq) {
;     f32x4 v = (f32x4){0.f, 0.f, 0.f, 0.f};
;     if (fq < n4) v = *(const f32x4*)(part + (size_t)row * pitch + 4 * fq);
;     float s = (v[0] + v[1]) + (v[2] + v[3]);
;     s += __shfl_xor(s, 16); s += __shfl_xor(s, 32);
;     return s;
; }
;     __device__ __forceinline__ void operator()(const f32x4 (&acc)[2][2][4][2], const Unit& u, int wr, int wc, int fr, int fq) const {
;         const int row0 = u.pm * BM + wr * 64 + fr, col0 = u.pn * 128 + wc * 32 + 8 * fq;
; #pragma unroll
;         for (int ai = 0; ai < 2; ++ai)
; #pragma unroll
;             for (int m = 0; m < 4; ++m) {
;                 const int row = row0 + ai * HALF + m * 16;
;                 const float rs = rsqrtf(row_ssq(ssq, 16, 4, row, fq) * (1.f / 1024.f) + EPS);
;                 float r[8];
; #pragma unroll
;                 for (int n = 0; n < 2; ++n)
; #pragma unroll
;                     for (int e = 0; e < 4; ++e) { const float gv = acc[ai][0][m][n][e] * rs, uv = acc[ai][1][m][n][e] * rs; r[n * 4 + e] = gv * fast_sigmoid(gv) * uv; }
;                 u32x4 w; w.x = pk2(r[0], r[1]); w.y = pk2(r[2], r[3]); w.z = pk2(r[4], r[5]); w.w = pk2(r[6], r[7]);
;                 *(u32x4*)(O + (size_t)row * DFF + col0) = w;
.LBB0_1154:
	v_and_b32_e32 v166, 48, v241
	v_lshl_add_u32 v166, v146, 6, v166
	v_add_u32_e32 v166, 0x24000, v166
	ds_read_b128 v[168:171], v166
	ds_read_b128 v[172:175], v166 offset:1024
	ds_read_b128 v[176:179], v166 offset:2048
	ds_read_b128 v[180:183], v166 offset:3072
	ds_read_b128 v[184:187], v166 offset:8192
	ds_read_b128 v[188:191], v166 offset:9216
	ds_read_b128 v[192:195], v166 offset:10240
	ds_read_b128 v[196:199], v166 offset:11264
	v_lshl_add_u32 v144, s39, 8, v146
	v_lshl_or_b32 v142, s4, 7, v148
	v_ashrrev_i32_e32 v143, 31, v142
	v_lshl_add_u64 v[142:143], v[142:143], 1, s[96:97]
	s_movk_i32 s4, 0x1600
	s_mov_b64 s[22:23], -1
	s_waitcnt lgkmcnt(7)
	v_add_f32_e32 v168, v169, v168
	v_add_f32_e32 v170, v170, v171
	v_add_f32_e32 v168, v168, v170
	v_mov_b32_e32 v169, v168
	s_waitcnt lgkmcnt(6)
	v_add_f32_e32 v172, v173, v172
	v_add_f32_e32 v174, v174, v175
	v_add_f32_e32 v172, v172, v174
	v_mov_b32_e32 v173, v172
	s_waitcnt lgkmcnt(5)
	v_add_f32_e32 v176, v177, v176
	v_add_f32_e32 v178, v178, v179
	v_add_f32_e32 v176, v176, v178
	v_mov_b32_e32 v177, v176
	s_waitcnt lgkmcnt(4)
	v_add_f32_e32 v180, v181, v180
	v_add_f32_e32 v182, v182, v183
	v_add_f32_e32 v180, v180, v182
	v_mov_b32_e32 v181, v180
	s_waitcnt lgkmcnt(3)
	v_add_f32_e32 v184, v185, v184
	v_add_f32_e32 v186, v186, v187
	v_add_f32_e32 v184, v184, v186
	v_mov_b32_e32 v185, v184
	s_waitcnt lgkmcnt(2)
	v_add_f32_e32 v188, v189, v188
	v_add_f32_e32 v190, v190, v191
	v_add_f32_e32 v188, v188, v190
	v_mov_b32_e32 v189, v188
	s_waitcnt lgkmcnt(1)
	v_add_f32_e32 v192, v193, v192
	v_add_f32_e32 v194, v194, v195
	v_add_f32_e32 v192, v192, v194
	v_mov_b32_e32 v193, v192
	s_waitcnt lgkmcnt(0)
	v_add_f32_e32 v196, v197, v196
	v_add_f32_e32 v198, v198, v199
	v_add_f32_e32 v196, v196, v198
	v_mov_b32_e32 v197, v196
	s_nop 1
	v_permlane16_swap_b32_e32 v168, v169
	v_permlane16_swap_b32_e32 v172, v173
	v_permlane16_swap_b32_e32 v176, v177
	v_permlane16_swap_b32_e32 v180, v181
	v_permlane16_swap_b32_e32 v184, v185
	v_permlane16_swap_b32_e32 v188, v189
	v_permlane16_swap_b32_e32 v192, v193
	v_permlane16_swap_b32_e32 v196, v197
	v_add_f32_e32 v168, v168, v169
	v_add_f32_e32 v172, v172, v173
	v_add_f32_e32 v176, v176, v177
	v_add_f32_e32 v180, v180, v181
	v_add_f32_e32 v184, v184, v185
	v_add_f32_e32 v188, v188, v189
	v_add_f32_e32 v192, v192, v193
	v_add_f32_e32 v196, v196, v197
	v_mov_b32_e32 v169, v168
	v_mov_b32_e32 v173, v172
	v_mov_b32_e32 v177, v176
	v_mov_b32_e32 v181, v180
	v_mov_b32_e32 v185, v184
	v_mov_b32_e32 v189, v188
	v_mov_b32_e32 v193, v192
	v_mov_b32_e32 v197, v196
	s_nop 1
	v_permlane32_swap_b32_e32 v168, v169
	v_permlane32_swap_b32_e32 v172, v173
	v_permlane32_swap_b32_e32 v176, v177
	v_permlane32_swap_b32_e32 v180, v181
	v_permlane32_swap_b32_e32 v184, v185
	v_permlane32_swap_b32_e32 v188, v189
	v_permlane32_swap_b32_e32 v192, v193
	v_permlane32_swap_b32_e32 v196, v197
	v_add_f32_e32 v168, v168, v169
	v_add_f32_e32 v172, v172, v173
	v_add_f32_e32 v176, v176, v177
	v_add_f32_e32 v180, v180, v181
	v_add_f32_e32 v184, v184, v185
	v_add_f32_e32 v188, v188, v189
	v_add_f32_e32 v192, v192, v193
	v_add_f32_e32 v196, v196, v197
	v_fmamk_f32 v168, v168, 0x3a800000, v239
	v_fmamk_f32 v172, v172, 0x3a800000, v239
	v_fmamk_f32 v176, v176, 0x3a800000, v239
	v_fmamk_f32 v180, v180, 0x3a800000, v239
	v_fmamk_f32 v184, v184, 0x3a800000, v239
	v_fmamk_f32 v188, v188, 0x3a800000, v239
	v_fmamk_f32 v192, v192, 0x3a800000, v239
	v_fmamk_f32 v196, v196, 0x3a800000, v239
	v_rsq_f32_e32 v158, v168
	v_rsq_f32_e32 v159, v172
	v_rsq_f32_e32 v160, v176
	v_rsq_f32_e32 v161, v180
	v_rsq_f32_e32 v162, v184
	v_rsq_f32_e32 v163, v188
	v_rsq_f32_e32 v164, v192
	v_rsq_f32_e32 v165, v196
	s_nop 0
	v_mov_b32_e32 v152, v158
	v_pk_mul_f32 v[126:127], v[126:127], v[152:153] op_sel_hi:[1,0]
	v_pk_mul_f32 v[118:119], v[118:119], v[152:153] op_sel_hi:[1,0]
	v_mul_f32_e32 v145, 0xbfb8aa3b, v126
	v_exp_f32_e32 v145, v145
	v_pk_mul_f32 v[120:121], v[120:121], v[152:153] op_sel_hi:[1,0]
	v_pk_mul_f32 v[122:123], v[122:123], v[152:153] op_sel_hi:[1,0]
	v_pk_mul_f32 v[114:115], v[114:115], v[152:153] op_sel_hi:[1,0]
	v_add_f32_e32 v145, 1.0, v145
	v_rcp_f32_e32 v154, v145
	v_mul_f32_e32 v145, 0xbfb8aa3b, v127
	v_exp_f32_e32 v145, v145
	v_pk_mul_f32 v[116:117], v[116:117], v[152:153] op_sel_hi:[1,0]
	v_add_f32_e32 v145, 1.0, v145
	v_rcp_f32_e32 v155, v145
	s_nop 0
	v_pk_mul_f32 v[126:127], v[126:127], v[154:155]
	s_nop 0
	v_pk_mul_f32 v[118:119], v[118:119], v[126:127]
	v_pk_mul_f32 v[126:127], v[128:129], v[152:153] op_sel_hi:[1,0]
	s_nop 0
	v_mul_f32_e32 v128, 0xbfb8aa3b, v126
	v_mul_f32_e32 v129, 0xbfb8aa3b, v127
	v_exp_f32_e32 v128, v128
	v_exp_f32_e32 v129, v129
	v_add_f32_e32 v128, 1.0, v128
	v_add_f32_e32 v129, 1.0, v129
	v_rcp_f32_e32 v128, v128
	v_rcp_f32_e32 v129, v129
	s_nop 0
	v_pk_mul_f32 v[126:127], v[126:127], v[128:129]
	s_nop 0
	v_pk_mul_f32 v[120:121], v[120:121], v[126:127]
	v_mul_f32_e32 v126, 0xbfb8aa3b, v122
	v_mul_f32_e32 v127, 0xbfb8aa3b, v123
	v_exp_f32_e32 v126, v126
	v_exp_f32_e32 v127, v127
	v_add_f32_e32 v126, 1.0, v126
	v_add_f32_e32 v127, 1.0, v127
	v_rcp_f32_e32 v126, v126
	v_rcp_f32_e32 v127, v127
	s_nop 0
	v_pk_mul_f32 v[122:123], v[122:123], v[126:127]
	s_nop 0
	v_pk_mul_f32 v[122:123], v[114:115], v[122:123]
	v_pk_mul_f32 v[114:115], v[124:125], v[152:153] op_sel_hi:[1,0]
	s_nop 0
	v_mul_f32_e32 v124, 0xbfb8aa3b, v114
	v_mul_f32_e32 v125, 0xbfb8aa3b, v115
	v_exp_f32_e32 v124, v124
	v_exp_f32_e32 v125, v125
	v_add_f32_e32 v124, 1.0, v124
	v_add_f32_e32 v125, 1.0, v125
	v_rcp_f32_e32 v124, v124
	v_rcp_f32_e32 v125, v125
	s_nop 0
	v_pk_mul_f32 v[114:115], v[114:115], v[124:125]
; __device__ __forceinline__ unsigned pk2(float lo, float hi) { f32x2_t v = {lo, hi}; bf16x2_t b = __builtin_convertvector(v, bf16x2_t); return __builtin_bit_cast(unsigned, b); }
; __device__ __forceinline__ float fast_sigmoid(float x) { return __builtin_amdgcn_rcpf(1.f + __expf(-x)); }
;     __device__ __forceinline__ void operator()(const f32x4 (&acc)[2][2][4][2], const Unit& u, int wr, int wc, int fr, int fq) const {
;     ...
;                 for (int n = 0; n < 2; ++n)
; #pragma unroll
;                     for (int e = 0; e < 4; ++e) { const float gv = acc[ai][0][m][n][e] * rs, uv = acc[ai][1][m][n][e] * rs; r[n * 4 + e] = gv * fast_sigmoid(gv) * uv; }
;                 u32x4 w; w.x = pk2(r[0], r[1]); w.y = pk2(r[2], r[3]); w.z = pk2(r[4], r[5]); w.w = pk2(r[6], r[7]);
;                 *(u32x4*)(O + (size_t)row * DFF + col0) = w;
	s_nop 0
	v_pk_mul_f32 v[124:125], v[116:117], v[114:115]
	v_cvt_pk_bf16_f32 v114, v118, v119
	v_cvt_pk_bf16_f32 v115, v120, v121
	v_cvt_pk_bf16_f32 v116, v122, v123
	v_cvt_pk_bf16_f32 v117, v124, v125
	v_mad_i64_i32 v[118:119], s[6:7], v144, s4, v[142:143]
	global_store_dwordx4 v[118:119], v[114:117], off
	s_nop 1
	v_or_b32_e32 v114, 16, v144
	v_mov_b32_e32 v116, v159
	v_pk_mul_f32 v[110:111], v[110:111], v[116:117] op_sel_hi:[1,0]
	v_pk_mul_f32 v[102:103], v[102:103], v[116:117] op_sel_hi:[1,0]
	v_mul_f32_e32 v115, 0xbfb8aa3b, v110
	v_exp_f32_e32 v115, v115
	v_pk_mul_f32 v[104:105], v[104:105], v[116:117] op_sel_hi:[1,0]
	v_pk_mul_f32 v[106:107], v[106:107], v[116:117] op_sel_hi:[1,0]
	v_pk_mul_f32 v[98:99], v[98:99], v[116:117] op_sel_hi:[1,0]
	v_add_f32_e32 v115, 1.0, v115
	v_rcp_f32_e32 v118, v115
	v_mul_f32_e32 v115, 0xbfb8aa3b, v111
	v_exp_f32_e32 v115, v115
	v_pk_mul_f32 v[100:101], v[100:101], v[116:117] op_sel_hi:[1,0]
	v_add_f32_e32 v115, 1.0, v115
	v_rcp_f32_e32 v119, v115
	s_nop 0
	v_pk_mul_f32 v[110:111], v[110:111], v[118:119]
	s_nop 0
	v_pk_mul_f32 v[102:103], v[102:103], v[110:111]
	v_pk_mul_f32 v[110:111], v[112:113], v[116:117] op_sel_hi:[1,0]
	s_nop 0
	v_mul_f32_e32 v112, 0xbfb8aa3b, v110
	v_mul_f32_e32 v113, 0xbfb8aa3b, v111
	v_exp_f32_e32 v112, v112
	v_exp_f32_e32 v113, v113
	v_add_f32_e32 v112, 1.0, v112
	v_add_f32_e32 v113, 1.0, v113
	v_rcp_f32_e32 v112, v112
	v_rcp_f32_e32 v113, v113
	s_nop 0
	v_pk_mul_f32 v[110:111], v[110:111], v[112:113]
	s_nop 0
	v_pk_mul_f32 v[104:105], v[104:105], v[110:111]
	v_mul_f32_e32 v110, 0xbfb8aa3b, v106
	v_mul_f32_e32 v111, 0xbfb8aa3b, v107
	v_exp_f32_e32 v110, v110
	v_exp_f32_e32 v111, v111
	v_add_f32_e32 v110, 1.0, v110
	v_add_f32_e32 v111, 1.0, v111
	v_rcp_f32_e32 v110, v110
	v_rcp_f32_e32 v111, v111
	s_nop 0
	v_pk_mul_f32 v[106:107], v[106:107], v[110:111]
	s_nop 0
	v_pk_mul_f32 v[106:107], v[98:99], v[106:107]
	v_pk_mul_f32 v[98:99], v[108:109], v[116:117] op_sel_hi:[1,0]
	s_nop 0
	v_mul_f32_e32 v108, 0xbfb8aa3b, v98
	v_mul_f32_e32 v109, 0xbfb8aa3b, v99
	v_exp_f32_e32 v108, v108
	v_exp_f32_e32 v109, v109
	v_add_f32_e32 v108, 1.0, v108
	v_add_f32_e32 v109, 1.0, v109
	v_rcp_f32_e32 v108, v108
	v_rcp_f32_e32 v109, v109
	s_nop 0
	v_pk_mul_f32 v[98:99], v[98:99], v[108:109]
	s_nop 0
	v_pk_mul_f32 v[108:109], v[100:101], v[98:99]
	v_cvt_pk_bf16_f32 v98, v102, v103
	v_cvt_pk_bf16_f32 v99, v104, v105
	v_cvt_pk_bf16_f32 v100, v106, v107
	v_cvt_pk_bf16_f32 v101, v108, v109
	v_mad_i64_i32 v[102:103], s[6:7], v114, s4, v[142:143]
	global_store_dwordx4 v[102:103], v[98:101], off
	s_nop 1
	v_or_b32_e32 v98, 32, v144
	v_mov_b32_e32 v100, v160
	v_pk_mul_f32 v[94:95], v[94:95], v[100:101] op_sel_hi:[1,0]
	v_pk_mul_f32 v[86:87], v[86:87], v[100:101] op_sel_hi:[1,0]
	v_mul_f32_e32 v99, 0xbfb8aa3b, v94
	v_exp_f32_e32 v99, v99
	v_pk_mul_f32 v[88:89], v[88:89], v[100:101] op_sel_hi:[1,0]
	v_pk_mul_f32 v[90:91], v[90:91], v[100:101] op_sel_hi:[1,0]
	v_pk_mul_f32 v[82:83], v[82:83], v[100:101] op_sel_hi:[1,0]
	v_add_f32_e32 v99, 1.0, v99
	v_rcp_f32_e32 v102, v99
	v_mul_f32_e32 v99, 0xbfb8aa3b, v95
	v_exp_f32_e32 v99, v99
	v_pk_mul_f32 v[84:85], v[84:85], v[100:101] op_sel_hi:[1,0]
	v_add_f32_e32 v99, 1.0, v99
	v_rcp_f32_e32 v103, v99
	s_nop 0
	v_pk_mul_f32 v[94:95], v[94:95], v[102:103]
	s_nop 0
	v_pk_mul_f32 v[86:87], v[86:87], v[94:95]
	v_pk_mul_f32 v[94:95], v[96:97], v[100:101] op_sel_hi:[1,0]
	s_nop 0
	v_mul_f32_e32 v96, 0xbfb8aa3b, v94
	v_mul_f32_e32 v97, 0xbfb8aa3b, v95
	v_exp_f32_e32 v96, v96
	v_exp_f32_e32 v97, v97
	v_add_f32_e32 v96, 1.0, v96
	v_add_f32_e32 v97, 1.0, v97
	v_rcp_f32_e32 v96, v96
	v_rcp_f32_e32 v97, v97
	s_nop 0
	v_pk_mul_f32 v[94:95], v[94:95], v[96:97]
	s_nop 0
	v_pk_mul_f32 v[88:89], v[88:89], v[94:95]
	v_mul_f32_e32 v94, 0xbfb8aa3b, v90
	v_mul_f32_e32 v95, 0xbfb8aa3b, v91
	v_exp_f32_e32 v94, v94
	v_exp_f32_e32 v95, v95
	v_add_f32_e32 v94, 1.0, v94
	v_add_f32_e32 v95, 1.0, v95
	v_rcp_f32_e32 v94, v94
	v_rcp_f32_e32 v95, v95
	s_nop 0
	v_pk_mul_f32 v[90:91], v[90:91], v[94:95]
	s_nop 0
	v_pk_mul_f32 v[90:91], v[82:83], v[90:91]
	v_pk_mul_f32 v[82:83], v[92:93], v[100:101] op_sel_hi:[1,0]
	s_nop 0
	v_mul_f32_e32 v92, 0xbfb8aa3b, v82
	v_mul_f32_e32 v93, 0xbfb8aa3b, v83
	v_exp_f32_e32 v92, v92
	v_exp_f32_e32 v93, v93
	v_add_f32_e32 v92, 1.0, v92
	v_add_f32_e32 v93, 1.0, v93
	v_rcp_f32_e32 v92, v92
	v_rcp_f32_e32 v93, v93
	s_nop 0
	v_pk_mul_f32 v[82:83], v[82:83], v[92:93]
	s_nop 0
	v_pk_mul_f32 v[92:93], v[84:85], v[82:83]
	v_cvt_pk_bf16_f32 v82, v86, v87
	v_cvt_pk_bf16_f32 v83, v88, v89
	v_cvt_pk_bf16_f32 v84, v90, v91
	v_cvt_pk_bf16_f32 v85, v92, v93
	v_mad_i64_i32 v[86:87], s[6:7], v98, s4, v[142:143]
	global_store_dwordx4 v[86:87], v[82:85], off
	s_nop 1
	v_or_b32_e32 v82, 48, v144
	v_mov_b32_e32 v84, v161
	v_pk_mul_f32 v[78:79], v[78:79], v[84:85] op_sel_hi:[1,0]
	v_pk_mul_f32 v[70:71], v[70:71], v[84:85] op_sel_hi:[1,0]
	v_mul_f32_e32 v83, 0xbfb8aa3b, v78
	v_exp_f32_e32 v83, v83
	v_pk_mul_f32 v[72:73], v[72:73], v[84:85] op_sel_hi:[1,0]
	v_pk_mul_f32 v[74:75], v[74:75], v[84:85] op_sel_hi:[1,0]
	v_pk_mul_f32 v[66:67], v[66:67], v[84:85] op_sel_hi:[1,0]
	v_add_f32_e32 v83, 1.0, v83
	v_rcp_f32_e32 v86, v83
	v_mul_f32_e32 v83, 0xbfb8aa3b, v79
	v_exp_f32_e32 v83, v83
	v_pk_mul_f32 v[68:69], v[68:69], v[84:85] op_sel_hi:[1,0]
	v_add_f32_e32 v83, 1.0, v83
	v_rcp_f32_e32 v87, v83
	s_nop 0
	v_pk_mul_f32 v[78:79], v[78:79], v[86:87]
	s_nop 0
	v_pk_mul_f32 v[70:71], v[70:71], v[78:79]
	v_pk_mul_f32 v[78:79], v[80:81], v[84:85] op_sel_hi:[1,0]
	s_nop 0
	v_mul_f32_e32 v80, 0xbfb8aa3b, v78
	v_mul_f32_e32 v81, 0xbfb8aa3b, v79
	v_exp_f32_e32 v80, v80
	v_exp_f32_e32 v81, v81
; __device__ __forceinline__ unsigned pk2(float lo, float hi) { f32x2_t v = {lo, hi}; bf16x2_t b = __builtin_convertvector(v, bf16x2_t); return __builtin_bit_cast(unsigned, b); }
; __device__ __forceinline__ float fast_sigmoid(float x) { return __builtin_amdgcn_rcpf(1.f + __expf(-x)); }
;     __device__ __forceinline__ void operator()(const f32x4 (&acc)[2][2][4][2], const Unit& u, int wr, int wc, int fr, int fq) const {
;     ...
;                 for (int n = 0; n < 2; ++n)
; #pragma unroll
;                     for (int e = 0; e < 4; ++e) { const float gv = acc[ai][0][m][n][e] * rs, uv = acc[ai][1][m][n][e] * rs; r[n * 4 + e] = gv * fast_sigmoid(gv) * uv; }
;                 u32x4 w; w.x = pk2(r[0], r[1]); w.y = pk2(r[2], r[3]); w.z = pk2(r[4], r[5]); w.w = pk2(r[6], r[7]);
;                 *(u32x4*)(O + (size_t)row * DFF + col0) = w;
	v_add_f32_e32 v80, 1.0, v80
	v_add_f32_e32 v81, 1.0, v81
	v_rcp_f32_e32 v80, v80
	v_rcp_f32_e32 v81, v81
	s_nop 0
	v_pk_mul_f32 v[78:79], v[78:79], v[80:81]
	s_nop 0
	v_pk_mul_f32 v[72:73], v[72:73], v[78:79]
	v_mul_f32_e32 v78, 0xbfb8aa3b, v74
	v_mul_f32_e32 v79, 0xbfb8aa3b, v75
	v_exp_f32_e32 v78, v78
	v_exp_f32_e32 v79, v79
	v_add_f32_e32 v78, 1.0, v78
	v_add_f32_e32 v79, 1.0, v79
	v_rcp_f32_e32 v78, v78
	v_rcp_f32_e32 v79, v79
	s_nop 0
	v_pk_mul_f32 v[74:75], v[74:75], v[78:79]
	s_nop 0
	v_pk_mul_f32 v[74:75], v[66:67], v[74:75]
	v_pk_mul_f32 v[66:67], v[76:77], v[84:85] op_sel_hi:[1,0]
	s_nop 0
	v_mul_f32_e32 v76, 0xbfb8aa3b, v66
	v_mul_f32_e32 v77, 0xbfb8aa3b, v67
	v_exp_f32_e32 v76, v76
	v_exp_f32_e32 v77, v77
	v_add_f32_e32 v76, 1.0, v76
	v_add_f32_e32 v77, 1.0, v77
	v_rcp_f32_e32 v76, v76
	v_rcp_f32_e32 v77, v77
	s_nop 0
	v_pk_mul_f32 v[66:67], v[66:67], v[76:77]
	s_nop 0
	v_pk_mul_f32 v[76:77], v[68:69], v[66:67]
	v_cvt_pk_bf16_f32 v66, v70, v71
	v_cvt_pk_bf16_f32 v67, v72, v73
	v_cvt_pk_bf16_f32 v68, v74, v75
	v_cvt_pk_bf16_f32 v69, v76, v77
	v_mad_i64_i32 v[70:71], s[6:7], v82, s4, v[142:143]
	global_store_dwordx4 v[70:71], v[66:69], off
	s_nop 1
	v_add_u32_e32 v66, 0x80, v144
	v_mov_b32_e32 v68, v162
	v_pk_mul_f32 v[62:63], v[62:63], v[68:69] op_sel_hi:[1,0]
	v_pk_mul_f32 v[54:55], v[54:55], v[68:69] op_sel_hi:[1,0]
	v_mul_f32_e32 v67, 0xbfb8aa3b, v62
	v_exp_f32_e32 v67, v67
	v_pk_mul_f32 v[56:57], v[56:57], v[68:69] op_sel_hi:[1,0]
	v_pk_mul_f32 v[58:59], v[58:59], v[68:69] op_sel_hi:[1,0]
	v_pk_mul_f32 v[50:51], v[50:51], v[68:69] op_sel_hi:[1,0]
	v_add_f32_e32 v67, 1.0, v67
	v_rcp_f32_e32 v70, v67
	v_mul_f32_e32 v67, 0xbfb8aa3b, v63
	v_exp_f32_e32 v67, v67
	v_pk_mul_f32 v[52:53], v[52:53], v[68:69] op_sel_hi:[1,0]
	v_add_f32_e32 v67, 1.0, v67
	v_rcp_f32_e32 v71, v67
	s_nop 0
	v_pk_mul_f32 v[62:63], v[62:63], v[70:71]
	s_nop 0
	v_pk_mul_f32 v[54:55], v[54:55], v[62:63]
	v_pk_mul_f32 v[62:63], v[64:65], v[68:69] op_sel_hi:[1,0]
	s_nop 0
	v_mul_f32_e32 v64, 0xbfb8aa3b, v62
	v_mul_f32_e32 v65, 0xbfb8aa3b, v63
	v_exp_f32_e32 v64, v64
	v_exp_f32_e32 v65, v65
	v_add_f32_e32 v64, 1.0, v64
	v_add_f32_e32 v65, 1.0, v65
	v_rcp_f32_e32 v64, v64
	v_rcp_f32_e32 v65, v65
	s_nop 0
	v_pk_mul_f32 v[62:63], v[62:63], v[64:65]
	s_nop 0
	v_pk_mul_f32 v[56:57], v[56:57], v[62:63]
	v_mul_f32_e32 v62, 0xbfb8aa3b, v58
	v_mul_f32_e32 v63, 0xbfb8aa3b, v59
	v_exp_f32_e32 v62, v62
	v_exp_f32_e32 v63, v63
	v_add_f32_e32 v62, 1.0, v62
	v_add_f32_e32 v63, 1.0, v63
	v_rcp_f32_e32 v62, v62
	v_rcp_f32_e32 v63, v63
	s_nop 0
	v_pk_mul_f32 v[58:59], v[58:59], v[62:63]
	s_nop 0
	v_pk_mul_f32 v[58:59], v[50:51], v[58:59]
	v_pk_mul_f32 v[50:51], v[60:61], v[68:69] op_sel_hi:[1,0]
	s_nop 0
	v_mul_f32_e32 v60, 0xbfb8aa3b, v50
	v_mul_f32_e32 v61, 0xbfb8aa3b, v51
	v_exp_f32_e32 v60, v60
	v_exp_f32_e32 v61, v61
	v_add_f32_e32 v60, 1.0, v60
	v_add_f32_e32 v61, 1.0, v61
	v_rcp_f32_e32 v60, v60
	v_rcp_f32_e32 v61, v61
	s_nop 0
	v_pk_mul_f32 v[50:51], v[50:51], v[60:61]
	s_nop 0
	v_pk_mul_f32 v[60:61], v[52:53], v[50:51]
	v_cvt_pk_bf16_f32 v50, v54, v55
	v_cvt_pk_bf16_f32 v51, v56, v57
	v_cvt_pk_bf16_f32 v52, v58, v59
	v_cvt_pk_bf16_f32 v53, v60, v61
	v_mad_i64_i32 v[54:55], s[6:7], v66, s4, v[142:143]
	global_store_dwordx4 v[54:55], v[50:53], off
	s_nop 1
	v_add_u32_e32 v50, 0x90, v144
	v_mov_b32_e32 v52, v163
	v_pk_mul_f32 v[46:47], v[46:47], v[52:53] op_sel_hi:[1,0]
	v_pk_mul_f32 v[38:39], v[38:39], v[52:53] op_sel_hi:[1,0]
	v_mul_f32_e32 v51, 0xbfb8aa3b, v46
	v_exp_f32_e32 v51, v51
	v_pk_mul_f32 v[40:41], v[40:41], v[52:53] op_sel_hi:[1,0]
	v_pk_mul_f32 v[42:43], v[42:43], v[52:53] op_sel_hi:[1,0]
	v_pk_mul_f32 v[34:35], v[34:35], v[52:53] op_sel_hi:[1,0]
	v_add_f32_e32 v51, 1.0, v51
	v_rcp_f32_e32 v54, v51
	v_mul_f32_e32 v51, 0xbfb8aa3b, v47
	v_exp_f32_e32 v51, v51
	v_pk_mul_f32 v[36:37], v[36:37], v[52:53] op_sel_hi:[1,0]
	v_add_f32_e32 v51, 1.0, v51
	v_rcp_f32_e32 v55, v51
	s_nop 0
	v_pk_mul_f32 v[46:47], v[46:47], v[54:55]
	s_nop 0
	v_pk_mul_f32 v[38:39], v[38:39], v[46:47]
	v_pk_mul_f32 v[46:47], v[48:49], v[52:53] op_sel_hi:[1,0]
	s_nop 0
	v_mul_f32_e32 v48, 0xbfb8aa3b, v46
	v_mul_f32_e32 v49, 0xbfb8aa3b, v47
	v_exp_f32_e32 v48, v48
	v_exp_f32_e32 v49, v49
	v_add_f32_e32 v48, 1.0, v48
	v_add_f32_e32 v49, 1.0, v49
	v_rcp_f32_e32 v48, v48
	v_rcp_f32_e32 v49, v49
	s_nop 0
	v_pk_mul_f32 v[46:47], v[46:47], v[48:49]
	s_nop 0
	v_pk_mul_f32 v[40:41], v[40:41], v[46:47]
	v_mul_f32_e32 v46, 0xbfb8aa3b, v42
	v_mul_f32_e32 v47, 0xbfb8aa3b, v43
	v_exp_f32_e32 v46, v46
	v_exp_f32_e32 v47, v47
	v_add_f32_e32 v46, 1.0, v46
	v_add_f32_e32 v47, 1.0, v47
	v_rcp_f32_e32 v46, v46
	v_rcp_f32_e32 v47, v47
	s_nop 0
	v_pk_mul_f32 v[42:43], v[42:43], v[46:47]
	s_nop 0
	v_pk_mul_f32 v[42:43], v[34:35], v[42:43]
	v_pk_mul_f32 v[34:35], v[44:45], v[52:53] op_sel_hi:[1,0]
	s_nop 0
	v_mul_f32_e32 v44, 0xbfb8aa3b, v34
; __device__ __forceinline__ unsigned pk2(float lo, float hi) { f32x2_t v = {lo, hi}; bf16x2_t b = __builtin_convertvector(v, bf16x2_t); return __builtin_bit_cast(unsigned, b); }
; __device__ __forceinline__ float fast_sigmoid(float x) { return __builtin_amdgcn_rcpf(1.f + __expf(-x)); }
; #define PG8_BAR __builtin_amdgcn_s_barrier()
; template <class Epi>
; __device__ __forceinline__ void gemm_phase(LAS unsigned char* lds, int wave_s, const Gemm g, const StaticOrder S, const Epi E) {
;     ...
;         if (wr == 0) PG8_BAR;
;         E(acc, cur, wr, wc, fr, fq);
;         if (!has_next) break;
; #pragma unroll
;         for (int a = 0; a < 2; ++a)
; #pragma unroll
;             for (int b = 0; b < 2; ++b)
; #pragma unroll
;                 for (int m = 0; m < 4; ++m)
; #pragma unroll
;                     for (int n = 0; n < 2; ++n) acc[a][b][m][n] = (f32x4){0.f, 0.f, 0.f, 0.f};
;         cur = nxt; cA = nA; cB = nB; ++ui;
;         if (wr == 1) PG8_BAR;
;     __device__ __forceinline__ void operator()(const f32x4 (&acc)[2][2][4][2], const Unit& u, int wr, int wc, int fr, int fq) const {
;     ...
;                 for (int n = 0; n < 2; ++n)
; #pragma unroll
;                     for (int e = 0; e < 4; ++e) { const float gv = acc[ai][0][m][n][e] * rs, uv = acc[ai][1][m][n][e] * rs; r[n * 4 + e] = gv * fast_sigmoid(gv) * uv; }
;                 u32x4 w; w.x = pk2(r[0], r[1]); w.y = pk2(r[2], r[3]); w.z = pk2(r[4], r[5]); w.w = pk2(r[6], r[7]);
;                 *(u32x4*)(O + (size_t)row * DFF + col0) = w;
	v_mul_f32_e32 v45, 0xbfb8aa3b, v35
	v_exp_f32_e32 v44, v44
	v_exp_f32_e32 v45, v45
	v_add_f32_e32 v44, 1.0, v44
	v_add_f32_e32 v45, 1.0, v45
	v_rcp_f32_e32 v44, v44
	v_rcp_f32_e32 v45, v45
	s_nop 0
	v_pk_mul_f32 v[34:35], v[34:35], v[44:45]
	s_nop 0
	v_pk_mul_f32 v[44:45], v[36:37], v[34:35]
	v_cvt_pk_bf16_f32 v34, v38, v39
	v_cvt_pk_bf16_f32 v35, v40, v41
	v_cvt_pk_bf16_f32 v36, v42, v43
	v_cvt_pk_bf16_f32 v37, v44, v45
	v_mad_i64_i32 v[38:39], s[6:7], v50, s4, v[142:143]
	global_store_dwordx4 v[38:39], v[34:37], off
	s_nop 1
	v_add_u32_e32 v34, 0xa0, v144
	v_mov_b32_e32 v36, v164
	v_pk_mul_f32 v[30:31], v[30:31], v[36:37] op_sel_hi:[1,0]
	v_pk_mul_f32 v[22:23], v[22:23], v[36:37] op_sel_hi:[1,0]
	v_mul_f32_e32 v35, 0xbfb8aa3b, v30
	v_exp_f32_e32 v35, v35
	v_pk_mul_f32 v[24:25], v[24:25], v[36:37] op_sel_hi:[1,0]
	v_pk_mul_f32 v[26:27], v[26:27], v[36:37] op_sel_hi:[1,0]
	v_pk_mul_f32 v[18:19], v[18:19], v[36:37] op_sel_hi:[1,0]
	v_add_f32_e32 v35, 1.0, v35
	v_rcp_f32_e32 v38, v35
	v_mul_f32_e32 v35, 0xbfb8aa3b, v31
	v_exp_f32_e32 v35, v35
	v_pk_mul_f32 v[20:21], v[20:21], v[36:37] op_sel_hi:[1,0]
	v_add_f32_e32 v35, 1.0, v35
	v_rcp_f32_e32 v39, v35
	s_nop 0
	v_pk_mul_f32 v[30:31], v[30:31], v[38:39]
	s_nop 0
	v_pk_mul_f32 v[22:23], v[22:23], v[30:31]
	v_pk_mul_f32 v[30:31], v[32:33], v[36:37] op_sel_hi:[1,0]
	s_nop 0
	v_mul_f32_e32 v32, 0xbfb8aa3b, v30
	v_mul_f32_e32 v33, 0xbfb8aa3b, v31
	v_exp_f32_e32 v32, v32
	v_exp_f32_e32 v33, v33
	v_add_f32_e32 v32, 1.0, v32
	v_add_f32_e32 v33, 1.0, v33
	v_rcp_f32_e32 v32, v32
	v_rcp_f32_e32 v33, v33
	s_nop 0
	v_pk_mul_f32 v[30:31], v[30:31], v[32:33]
	s_nop 0
	v_pk_mul_f32 v[24:25], v[24:25], v[30:31]
	v_mul_f32_e32 v30, 0xbfb8aa3b, v26
	v_mul_f32_e32 v31, 0xbfb8aa3b, v27
	v_exp_f32_e32 v30, v30
	v_exp_f32_e32 v31, v31
	v_add_f32_e32 v30, 1.0, v30
	v_add_f32_e32 v31, 1.0, v31
	v_rcp_f32_e32 v30, v30
	v_rcp_f32_e32 v31, v31
	s_nop 0
	v_pk_mul_f32 v[26:27], v[26:27], v[30:31]
	s_nop 0
	v_pk_mul_f32 v[26:27], v[18:19], v[26:27]
	v_pk_mul_f32 v[18:19], v[28:29], v[36:37] op_sel_hi:[1,0]
	s_nop 0
	v_mul_f32_e32 v28, 0xbfb8aa3b, v18
	v_mul_f32_e32 v29, 0xbfb8aa3b, v19
	v_exp_f32_e32 v28, v28
	v_exp_f32_e32 v29, v29
	v_add_f32_e32 v28, 1.0, v28
	v_add_f32_e32 v29, 1.0, v29
	v_rcp_f32_e32 v28, v28
	v_rcp_f32_e32 v29, v29
	s_nop 0
	v_pk_mul_f32 v[18:19], v[18:19], v[28:29]
	s_nop 0
	v_pk_mul_f32 v[28:29], v[20:21], v[18:19]
	v_cvt_pk_bf16_f32 v18, v22, v23
	v_cvt_pk_bf16_f32 v19, v24, v25
	v_cvt_pk_bf16_f32 v20, v26, v27
	v_cvt_pk_bf16_f32 v21, v28, v29
	v_mad_i64_i32 v[22:23], s[6:7], v34, s4, v[142:143]
	global_store_dwordx4 v[22:23], v[18:21], off
	s_nop 1
	v_add_u32_e32 v18, 0xb0, v144
	v_mov_b32_e32 v20, v165
	v_pk_mul_f32 v[14:15], v[14:15], v[20:21] op_sel_hi:[1,0]
	v_pk_mul_f32 v[6:7], v[6:7], v[20:21] op_sel_hi:[1,0]
	v_mul_f32_e32 v19, 0xbfb8aa3b, v14
	v_exp_f32_e32 v19, v19
	v_pk_mul_f32 v[8:9], v[8:9], v[20:21] op_sel_hi:[1,0]
	v_pk_mul_f32 v[10:11], v[10:11], v[20:21] op_sel_hi:[1,0]
	v_pk_mul_f32 v[2:3], v[2:3], v[20:21] op_sel_hi:[1,0]
	v_add_f32_e32 v19, 1.0, v19
	v_rcp_f32_e32 v22, v19
	v_mul_f32_e32 v19, 0xbfb8aa3b, v15
	v_exp_f32_e32 v19, v19
	v_pk_mul_f32 v[4:5], v[4:5], v[20:21] op_sel_hi:[1,0]
	s_andn2_b64 vcc, exec, s[42:43]
	v_add_f32_e32 v19, 1.0, v19
	v_rcp_f32_e32 v23, v19
	s_nop 0
	v_pk_mul_f32 v[14:15], v[14:15], v[22:23]
	s_nop 0
	v_pk_mul_f32 v[6:7], v[6:7], v[14:15]
	v_pk_mul_f32 v[14:15], v[16:17], v[20:21] op_sel_hi:[1,0]
	s_nop 0
	v_mul_f32_e32 v16, 0xbfb8aa3b, v14
	v_mul_f32_e32 v17, 0xbfb8aa3b, v15
	v_exp_f32_e32 v16, v16
	v_exp_f32_e32 v17, v17
	v_add_f32_e32 v16, 1.0, v16
	v_add_f32_e32 v17, 1.0, v17
	v_rcp_f32_e32 v16, v16
	v_rcp_f32_e32 v17, v17
	s_nop 0
	v_pk_mul_f32 v[14:15], v[14:15], v[16:17]
	s_nop 0
	v_pk_mul_f32 v[8:9], v[8:9], v[14:15]
	v_mul_f32_e32 v14, 0xbfb8aa3b, v10
	v_mul_f32_e32 v15, 0xbfb8aa3b, v11
	v_exp_f32_e32 v14, v14
	v_exp_f32_e32 v15, v15
	v_add_f32_e32 v14, 1.0, v14
	v_add_f32_e32 v15, 1.0, v15
	v_rcp_f32_e32 v14, v14
	v_rcp_f32_e32 v15, v15
	s_nop 0
	v_pk_mul_f32 v[10:11], v[10:11], v[14:15]
	s_nop 0
	v_pk_mul_f32 v[10:11], v[2:3], v[10:11]
	v_pk_mul_f32 v[2:3], v[12:13], v[20:21] op_sel_hi:[1,0]
	s_nop 0
	v_mul_f32_e32 v12, 0xbfb8aa3b, v2
	v_mul_f32_e32 v13, 0xbfb8aa3b, v3
	v_exp_f32_e32 v12, v12
	v_exp_f32_e32 v13, v13
	v_add_f32_e32 v12, 1.0, v12
	v_add_f32_e32 v13, 1.0, v13
	v_rcp_f32_e32 v12, v12
	v_rcp_f32_e32 v13, v13
	s_nop 0
	v_pk_mul_f32 v[2:3], v[2:3], v[12:13]
	s_nop 0
	v_pk_mul_f32 v[12:13], v[4:5], v[2:3]
	v_cvt_pk_bf16_f32 v2, v6, v7
	v_cvt_pk_bf16_f32 v3, v8, v9
	v_cvt_pk_bf16_f32 v4, v10, v11
	v_cvt_pk_bf16_f32 v5, v12, v13
	v_mad_i64_i32 v[6:7], s[6:7], v18, s4, v[142:143]
	global_store_dwordx4 v[6:7], v[2:5], off
	s_cbranch_vccnz .LBB0_1147
	s_andn2_b64 vcc, exec, s[0:1]
	s_cbranch_vccnz .LBB0_1146
	s_barrier
	s_branch .LBB0_1146
